# write-through (sc1) on the 16-byte short-conv MIX stores in P6
# speedup vs baseline: 1.0562x; 1.0012x over previous
.LBB0_758:
	v_ashrrev_i32_e32 v88, 6, v26
	v_cmp_gt_i32_e32 vcc, s46, v88
	v_ashrrev_i32_e32 v89, 31, v88
	s_nop 0
	v_cndmask_b32_e32 v27, v1, v90, vcc
	v_and_b32_e32 v93, v27, v88
	v_cmp_ne_u32_e64 s[8:9], v93, v27
	v_add_u32_e32 v27, s27, v26
	v_cmp_ne_u32_e32 vcc, 0, v93
	v_ashrrev_i32_e32 v86, 6, v27
	v_cmp_gt_i32_e64 s[6:7], s26, v27
	v_subbrev_co_u32_e32 v28, vcc, 0, v88, vcc
	v_addc_co_u32_e64 v30, vcc, 0, v88, s[8:9]
	v_cndmask_b32_e64 v26, 0, v86, s[6:7]
	v_cmp_gt_i32_e32 vcc, s46, v26
	v_ashrrev_i32_e32 v29, 31, v28
	v_lshlrev_b64 v[28:29], 10, v[28:29]
	v_cndmask_b32_e32 v87, v1, v90, vcc
	v_ashrrev_i32_e32 v31, 31, v30
	v_and_b32_e32 v103, v87, v26
	v_lshl_add_u64 v[28:29], v[74:75], 0, v[28:29]
	v_lshlrev_b64 v[30:31], 10, v[30:31]
	v_cmp_ne_u32_e64 s[10:11], 0, v103
	v_lshl_add_u64 v[30:31], v[74:75], 0, v[30:31]
	global_load_dwordx4 v[104:107], v[28:29], off
	global_load_dwordx4 v[108:111], v[30:31], off
	v_subbrev_co_u32_e64 v28, vcc, 0, v26, s[10:11]
	v_ashrrev_i32_e32 v29, 31, v28
	v_lshlrev_b64 v[28:29], 10, v[28:29]
	v_add_u32_e32 v27, s27, v27
	v_lshl_add_u64 v[28:29], v[74:75], 0, v[28:29]
	v_ashrrev_i32_e32 v84, 6, v27
	v_cmp_gt_i32_e64 s[4:5], s26, v27
	global_load_dwordx4 v[112:115], v[28:29], off
	v_add_u32_e32 v27, s27, v27
	v_cndmask_b32_e64 v28, 0, v84, s[4:5]
	v_cmp_gt_i32_e32 vcc, s46, v28
	v_ashrrev_i32_e32 v82, 6, v27
	v_cmp_gt_i32_e64 s[0:1], s26, v27
	v_cndmask_b32_e32 v85, v1, v90, vcc
	v_and_b32_e32 v99, v85, v28
	v_cmp_ne_u32_e64 s[12:13], 0, v99
	v_add_u32_e32 v91, s27, v27
	v_ashrrev_i32_e32 v80, 6, v91
	v_subbrev_co_u32_e64 v30, vcc, 0, v28, s[12:13]
	v_ashrrev_i32_e32 v31, 31, v30
	v_lshlrev_b64 v[30:31], 10, v[30:31]
	v_lshl_add_u64 v[30:31], v[74:75], 0, v[30:31]
	global_load_dwordx4 v[116:119], v[30:31], off
	v_cndmask_b32_e64 v30, 0, v82, s[0:1]
	v_cmp_gt_i32_e32 vcc, s46, v30
	v_ashrrev_i32_e32 v27, 31, v26
	v_ashrrev_i32_e32 v29, 31, v28
	v_cndmask_b32_e32 v83, v1, v90, vcc
	v_and_b32_e32 v95, v83, v30
	v_cmp_ne_u32_e64 s[14:15], 0, v95
	v_ashrrev_i32_e32 v31, 31, v30
	s_waitcnt vmcnt(2)
	v_cndmask_b32_e64 v140, 0, v111, s[8:9]
	v_subbrev_co_u32_e64 v32, vcc, 0, v30, s[14:15]
	v_cmp_gt_i32_e32 vcc, s26, v91
	v_ashrrev_i32_e32 v33, 31, v32
	v_lshlrev_b64 v[32:33], 10, v[32:33]
	v_cndmask_b32_e32 v34, 0, v80, vcc
	v_cmp_gt_i32_e64 s[18:19], s46, v34
	v_lshl_add_u64 v[32:33], v[74:75], 0, v[32:33]
	global_load_dwordx4 v[120:123], v[32:33], off
	v_cndmask_b32_e64 v81, v1, v90, s[18:19]
	v_and_b32_e32 v92, v81, v34
	v_cmp_ne_u32_e64 s[18:19], 0, v92
	v_ashrrev_i32_e32 v35, 31, v34
	v_cndmask_b32_e64 v141, 0, v110, s[8:9]
	v_subbrev_co_u32_e64 v32, s[20:21], 0, v34, s[18:19]
	v_ashrrev_i32_e32 v33, 31, v32
	v_lshlrev_b64 v[32:33], 10, v[32:33]
	v_lshl_add_u64 v[32:33], v[74:75], 0, v[32:33]
	global_load_dwordx4 v[124:127], v[32:33], off
	v_lshlrev_b64 v[32:33], 10, v[88:89]
	v_lshl_add_u64 v[36:37], v[74:75], 0, v[32:33]
	v_lshl_add_u64 v[32:33], v[76:77], 0, v[32:33]
	v_cmp_ne_u32_e64 s[20:21], v103, v87
	global_load_dwordx4 v[128:131], v[36:37], off
	global_load_dwordx4 v[132:135], v[32:33], off
	v_lshlrev_b64 v[32:33], 10, v[26:27]
	v_addc_co_u32_e64 v26, s[20:21], 0, v26, s[20:21]
	v_ashrrev_i32_e32 v27, 31, v26
	v_lshlrev_b64 v[26:27], 10, v[26:27]
	v_lshl_add_u64 v[36:37], v[74:75], 0, v[32:33]
	v_lshl_add_u64 v[26:27], v[74:75], 0, v[26:27]
	v_lshl_add_u64 v[32:33], v[76:77], 0, v[32:33]
	global_load_dwordx4 v[66:69], v[36:37], off
	global_load_dwordx4 v[62:65], v[32:33], off
	global_load_dwordx4 v[70:73], v[26:27], off
	v_lshlrev_b64 v[26:27], 10, v[28:29]
	v_lshl_add_u64 v[32:33], v[74:75], 0, v[26:27]
	v_lshl_add_u64 v[26:27], v[76:77], 0, v[26:27]
	v_cmp_ne_u32_e64 s[20:21], v99, v85
	global_load_dwordx4 v[54:57], v[32:33], off
	global_load_dwordx4 v[50:53], v[26:27], off
	v_addc_co_u32_e64 v26, s[20:21], 0, v28, s[20:21]
	v_ashrrev_i32_e32 v27, 31, v26
	v_lshlrev_b64 v[26:27], 10, v[26:27]
	v_lshl_add_u64 v[26:27], v[74:75], 0, v[26:27]
	global_load_dwordx4 v[58:61], v[26:27], off
	v_lshlrev_b64 v[26:27], 10, v[30:31]
	v_lshl_add_u64 v[28:29], v[74:75], 0, v[26:27]
	v_lshl_add_u64 v[26:27], v[76:77], 0, v[26:27]
	v_cmp_ne_u32_e64 s[20:21], v95, v83
	global_load_dwordx4 v[42:45], v[28:29], off
	global_load_dwordx4 v[38:41], v[26:27], off
	v_addc_co_u32_e64 v26, s[20:21], 0, v30, s[20:21]
	v_ashrrev_i32_e32 v27, 31, v26
	v_lshlrev_b64 v[26:27], 10, v[26:27]
	v_lshl_add_u64 v[26:27], v[74:75], 0, v[26:27]
	v_cmp_ne_u32_e64 s[20:21], v92, v81
	global_load_dwordx4 v[46:49], v[26:27], off
	v_lshlrev_b64 v[26:27], 10, v[34:35]
	v_addc_co_u32_e64 v34, s[20:21], 0, v34, s[20:21]
	v_ashrrev_i32_e32 v35, 31, v34
	v_lshlrev_b64 v[34:35], 10, v[34:35]
	v_lshl_add_u64 v[28:29], v[74:75], 0, v[26:27]
	v_lshl_add_u64 v[26:27], v[76:77], 0, v[26:27]
	v_lshl_add_u64 v[34:35], v[74:75], 0, v[34:35]
	global_load_dwordx4 v[30:33], v[28:29], off
	s_nop 0
	global_load_dwordx4 v[26:29], v[26:27], off
	v_cmp_eq_u32_e64 s[20:21], 0, v93
	global_load_dwordx4 v[34:37], v[34:35], off
	s_waitcnt vmcnt(17)
	v_cndmask_b32_e64 v110, 0, v113, s[10:11]
	v_cndmask_b32_e64 v139, v104, 0, s[20:21]
	v_cndmask_b32_e64 v111, 0, v112, s[10:11]
	v_lshlrev_b32_e32 v112, 16, v139
	v_and_b32_e32 v113, 0xffff0000, v139
	v_cndmask_b32_e64 v138, v105, 0, s[20:21]
	v_cndmask_b32_e64 v142, 0, v109, s[8:9]
	v_cndmask_b32_e64 v143, 0, v108, s[8:9]
	v_cndmask_b32_e64 v108, 0, v115, s[10:11]
	v_cndmask_b32_e64 v109, 0, v114, s[10:11]
	v_pk_mul_f32 v[112:113], v[6:7], v[112:113]
	v_cndmask_b32_e64 v136, v107, 0, s[20:21]
	v_cndmask_b32_e64 v137, v106, 0, s[20:21]
	s_waitcnt vmcnt(16)
	v_cndmask_b32_e64 v106, 0, v117, s[12:13]
	v_cndmask_b32_e64 v107, 0, v116, s[12:13]
	v_lshlrev_b32_e32 v116, 16, v143
	v_and_b32_e32 v117, 0xffff0000, v143
	v_cndmask_b32_e64 v104, 0, v119, s[12:13]
	v_cndmask_b32_e64 v105, 0, v118, s[12:13]
	s_waitcnt vmcnt(15)
	v_cndmask_b32_e64 v101, 0, v121, s[14:15]
	v_cndmask_b32_e64 v102, 0, v120, s[14:15]
	v_cndmask_b32_e64 v98, 0, v123, s[14:15]
	v_cndmask_b32_e64 v100, 0, v122, s[14:15]
	v_lshlrev_b64 v[88:89], 11, v[88:89]
	v_lshl_add_u64 v[88:89], v[78:79], 0, v[88:89]
	s_waitcnt vmcnt(14)
	v_cndmask_b32_e64 v96, 0, v125, s[18:19]
	v_cndmask_b32_e64 v97, 0, v124, s[18:19]
	v_cndmask_b32_e64 v93, 0, v127, s[18:19]
	v_cndmask_b32_e64 v94, 0, v126, s[18:19]
	s_waitcnt vmcnt(13)
	v_lshlrev_b32_e32 v114, 16, v128
	v_and_b32_e32 v115, 0xffff0000, v128
	v_pk_fma_f32 v[112:113], v[14:15], v[114:115], v[112:113]
	v_lshlrev_b32_e32 v114, 16, v138
	v_and_b32_e32 v115, 0xffff0000, v138
	s_waitcnt vmcnt(12)
	v_lshlrev_b32_e32 v118, 16, v132
	v_and_b32_e32 v119, 0xffff0000, v132
	v_pk_fma_f32 v[112:113], v[18:19], v[116:117], v[112:113]
	v_lshlrev_b32_e32 v116, 16, v129
	v_and_b32_e32 v117, 0xffff0000, v129
	v_pk_mul_f32 v[114:115], v[8:9], v[114:115]
	v_pk_mul_f32 v[112:113], v[112:113], v[118:119]
	v_lshlrev_b32_e32 v118, 16, v142
	v_and_b32_e32 v119, 0xffff0000, v142
	v_pk_fma_f32 v[114:115], v[16:17], v[116:117], v[114:115]
	v_lshlrev_b32_e32 v116, 16, v137
	v_and_b32_e32 v117, 0xffff0000, v137
	v_lshlrev_b32_e32 v120, 16, v133
	v_and_b32_e32 v121, 0xffff0000, v133
	v_pk_fma_f32 v[114:115], v[20:21], v[118:119], v[114:115]
	v_lshlrev_b32_e32 v118, 16, v130
	v_and_b32_e32 v119, 0xffff0000, v130
	v_pk_mul_f32 v[116:117], v[2:3], v[116:117]
	v_pk_mul_f32 v[114:115], v[114:115], v[120:121]
	v_lshlrev_b32_e32 v120, 16, v141
	v_and_b32_e32 v121, 0xffff0000, v141
	v_pk_fma_f32 v[116:117], v[10:11], v[118:119], v[116:117]
	v_lshlrev_b32_e32 v118, 16, v136
	v_and_b32_e32 v119, 0xffff0000, v136
	v_lshlrev_b32_e32 v122, 16, v134
	v_and_b32_e32 v123, 0xffff0000, v134
	v_pk_fma_f32 v[116:117], v[22:23], v[120:121], v[116:117]
	v_lshlrev_b32_e32 v120, 16, v131
	v_and_b32_e32 v121, 0xffff0000, v131
	v_pk_mul_f32 v[118:119], v[4:5], v[118:119]
	v_pk_mul_f32 v[116:117], v[116:117], v[122:123]
	v_lshlrev_b32_e32 v122, 16, v140
	v_and_b32_e32 v123, 0xffff0000, v140
	v_pk_fma_f32 v[118:119], v[12:13], v[120:121], v[118:119]
	v_lshlrev_b32_e32 v124, 16, v135
	v_and_b32_e32 v125, 0xffff0000, v135
	v_pk_fma_f32 v[118:119], v[24:25], v[122:123], v[118:119]
	v_cvt_pk_bf16_f32 v112, v112, v113
	v_pk_mul_f32 v[118:119], v[118:119], v[124:125]
	v_cvt_pk_bf16_f32 v113, v114, v115
	v_cvt_pk_bf16_f32 v114, v116, v117
	v_cvt_pk_bf16_f32 v115, v118, v119
	global_store_dwordx4 v[88:89], v[112:115], off offset:1024 sc1
	s_and_saveexec_b64 s[8:9], s[6:7]
	s_cbranch_execz .LBB0_757
	v_cmp_ne_u32_e64 s[6:7], v103, v87
	s_waitcnt vmcnt(11)
	v_lshlrev_b32_e32 v112, 16, v62
	v_and_b32_e32 v113, 0xffff0000, v62
	s_waitcnt vmcnt(10)
	v_cndmask_b32_e64 v114, 0, v71, s[6:7]
	v_cndmask_b32_e64 v89, 0, v70, s[6:7]
	v_lshlrev_b32_e32 v70, 16, v111
	v_and_b32_e32 v71, 0xffff0000, v111
	v_cndmask_b32_e64 v87, 0, v73, s[6:7]
	v_cndmask_b32_e64 v103, 0, v72, s[6:7]
	v_lshlrev_b32_e32 v72, 16, v66
	v_and_b32_e32 v73, 0xffff0000, v66
	v_pk_mul_f32 v[70:71], v[6:7], v[70:71]
	v_lshlrev_b32_e32 v88, 16, v89
	v_pk_fma_f32 v[70:71], v[14:15], v[72:73], v[70:71]
	v_lshlrev_b32_e32 v72, 16, v110
	v_and_b32_e32 v73, 0xffff0000, v110
	v_and_b32_e32 v89, 0xffff0000, v89
	v_lshlrev_b32_e32 v66, 16, v67
	v_and_b32_e32 v67, 0xffff0000, v67
	v_pk_mul_f32 v[72:73], v[8:9], v[72:73]
	v_pk_fma_f32 v[70:71], v[18:19], v[88:89], v[70:71]
	v_lshlrev_b32_e32 v88, 16, v114
	v_and_b32_e32 v89, 0xffff0000, v114
	v_pk_fma_f32 v[66:67], v[16:17], v[66:67], v[72:73]
	v_lshlrev_b32_e32 v62, 16, v63
	v_and_b32_e32 v63, 0xffff0000, v63
	v_pk_fma_f32 v[66:67], v[20:21], v[88:89], v[66:67]
	v_lshlrev_b32_e32 v72, 16, v68
	v_pk_mul_f32 v[66:67], v[66:67], v[62:63]
	v_lshlrev_b32_e32 v62, 16, v109
	v_and_b32_e32 v63, 0xffff0000, v109
	v_and_b32_e32 v73, 0xffff0000, v68
	v_pk_mul_f32 v[62:63], v[2:3], v[62:63]
	v_lshlrev_b32_e32 v88, 16, v103
	v_and_b32_e32 v89, 0xffff0000, v103
	v_pk_fma_f32 v[62:63], v[10:11], v[72:73], v[62:63]
	v_lshlrev_b32_e32 v110, 16, v64
	v_and_b32_e32 v111, 0xffff0000, v64
	v_pk_fma_f32 v[62:63], v[22:23], v[88:89], v[62:63]
	v_lshlrev_b32_e32 v68, 16, v69
	v_pk_mul_f32 v[72:73], v[62:63], v[110:111]
	v_lshlrev_b32_e32 v62, 16, v108
	v_and_b32_e32 v63, 0xffff0000, v108
	v_and_b32_e32 v69, 0xffff0000, v69
	v_pk_mul_f32 v[62:63], v[4:5], v[62:63]
	v_lshlrev_b32_e32 v88, 16, v87
	v_and_b32_e32 v89, 0xffff0000, v87
	v_pk_fma_f32 v[62:63], v[12:13], v[68:69], v[62:63]
	v_lshlrev_b32_e32 v64, 16, v65
	v_and_b32_e32 v65, 0xffff0000, v65
	v_pk_fma_f32 v[62:63], v[24:25], v[88:89], v[62:63]
	v_ashrrev_i32_e32 v87, 31, v86
	v_pk_mul_f32 v[70:71], v[70:71], v[112:113]
	v_pk_mul_f32 v[68:69], v[62:63], v[64:65]
	v_cvt_pk_bf16_f32 v63, v66, v67
	v_lshlrev_b64 v[66:67], 11, v[86:87]
	v_cvt_pk_bf16_f32 v62, v70, v71
	v_cvt_pk_bf16_f32 v64, v72, v73
	v_cvt_pk_bf16_f32 v65, v68, v69
	v_lshl_add_u64 v[66:67], v[78:79], 0, v[66:67]
	global_store_dwordx4 v[66:67], v[62:65], off offset:1024 sc1
	s_and_b64 exec, exec, s[4:5]
	s_cbranch_execz .LBB0_757
	v_cmp_ne_u32_e64 s[4:5], v99, v85
	s_waitcnt vmcnt(9)
	v_lshlrev_b32_e32 v64, 16, v50
	v_and_b32_e32 v65, 0xffff0000, v50
	s_waitcnt vmcnt(8)
	v_cndmask_b32_e64 v68, 0, v59, s[4:5]
	v_cndmask_b32_e64 v63, 0, v58, s[4:5]
	v_lshlrev_b32_e32 v58, 16, v107
	v_and_b32_e32 v59, 0xffff0000, v107
	v_cndmask_b32_e64 v66, 0, v61, s[4:5]
	v_cndmask_b32_e64 v67, 0, v60, s[4:5]
	v_lshlrev_b32_e32 v60, 16, v54
	v_and_b32_e32 v61, 0xffff0000, v54
	v_pk_mul_f32 v[58:59], v[6:7], v[58:59]
	v_lshlrev_b32_e32 v62, 16, v63
	v_pk_fma_f32 v[58:59], v[14:15], v[60:61], v[58:59]
	v_lshlrev_b32_e32 v60, 16, v106
	v_and_b32_e32 v61, 0xffff0000, v106
	v_and_b32_e32 v63, 0xffff0000, v63
	v_lshlrev_b32_e32 v54, 16, v55
	v_and_b32_e32 v55, 0xffff0000, v55
	v_pk_mul_f32 v[60:61], v[8:9], v[60:61]
	v_pk_fma_f32 v[58:59], v[18:19], v[62:63], v[58:59]
	v_lshlrev_b32_e32 v62, 16, v68
	v_and_b32_e32 v63, 0xffff0000, v68
	v_pk_fma_f32 v[54:55], v[16:17], v[54:55], v[60:61]
	v_lshlrev_b32_e32 v50, 16, v51
	v_and_b32_e32 v51, 0xffff0000, v51
	v_pk_fma_f32 v[54:55], v[20:21], v[62:63], v[54:55]
	v_lshlrev_b32_e32 v60, 16, v56
	v_pk_mul_f32 v[54:55], v[54:55], v[50:51]
	v_lshlrev_b32_e32 v50, 16, v105
	v_and_b32_e32 v51, 0xffff0000, v105
	v_and_b32_e32 v61, 0xffff0000, v56
	v_pk_mul_f32 v[50:51], v[2:3], v[50:51]
	v_lshlrev_b32_e32 v62, 16, v67
	v_and_b32_e32 v63, 0xffff0000, v67
	v_pk_fma_f32 v[50:51], v[10:11], v[60:61], v[50:51]
	v_pk_mul_f32 v[58:59], v[58:59], v[64:65]
	v_lshlrev_b32_e32 v64, 16, v52
	v_and_b32_e32 v65, 0xffff0000, v52
	v_pk_fma_f32 v[50:51], v[22:23], v[62:63], v[50:51]
	v_lshlrev_b32_e32 v56, 16, v57
	v_pk_mul_f32 v[60:61], v[50:51], v[64:65]
	v_lshlrev_b32_e32 v50, 16, v104
	v_and_b32_e32 v51, 0xffff0000, v104
	v_and_b32_e32 v57, 0xffff0000, v57
	v_pk_mul_f32 v[50:51], v[4:5], v[50:51]
	v_lshlrev_b32_e32 v62, 16, v66
	v_and_b32_e32 v63, 0xffff0000, v66
	v_pk_fma_f32 v[50:51], v[12:13], v[56:57], v[50:51]
	v_lshlrev_b32_e32 v52, 16, v53
	v_and_b32_e32 v53, 0xffff0000, v53
	v_pk_fma_f32 v[50:51], v[24:25], v[62:63], v[50:51]
	v_ashrrev_i32_e32 v85, 31, v84
	v_pk_mul_f32 v[56:57], v[50:51], v[52:53]
	v_cvt_pk_bf16_f32 v51, v54, v55
	v_lshlrev_b64 v[54:55], 11, v[84:85]
	v_cvt_pk_bf16_f32 v50, v58, v59
	v_cvt_pk_bf16_f32 v52, v60, v61
	v_cvt_pk_bf16_f32 v53, v56, v57
	v_lshl_add_u64 v[54:55], v[78:79], 0, v[54:55]
	global_store_dwordx4 v[54:55], v[50:53], off offset:1024 sc1
	s_and_b64 exec, exec, s[0:1]
	s_cbranch_execz .LBB0_757
	v_cmp_ne_u32_e64 s[0:1], v95, v83
	s_waitcnt vmcnt(7)
	v_lshlrev_b32_e32 v52, 16, v38
	v_and_b32_e32 v53, 0xffff0000, v38
	s_waitcnt vmcnt(6)
	v_cndmask_b32_e64 v56, 0, v47, s[0:1]
	v_cndmask_b32_e64 v51, 0, v46, s[0:1]
	v_lshlrev_b32_e32 v46, 16, v102
	v_and_b32_e32 v47, 0xffff0000, v102
	v_cndmask_b32_e64 v54, 0, v49, s[0:1]
	v_cndmask_b32_e64 v55, 0, v48, s[0:1]
	v_lshlrev_b32_e32 v48, 16, v42
	v_and_b32_e32 v49, 0xffff0000, v42
	v_pk_mul_f32 v[46:47], v[6:7], v[46:47]
	v_lshlrev_b32_e32 v50, 16, v51
	v_pk_fma_f32 v[46:47], v[14:15], v[48:49], v[46:47]
	v_lshlrev_b32_e32 v48, 16, v101
	v_and_b32_e32 v49, 0xffff0000, v101
	v_and_b32_e32 v51, 0xffff0000, v51
	v_lshlrev_b32_e32 v42, 16, v43
	v_and_b32_e32 v43, 0xffff0000, v43
	v_pk_mul_f32 v[48:49], v[8:9], v[48:49]
	v_pk_fma_f32 v[46:47], v[18:19], v[50:51], v[46:47]
	v_lshlrev_b32_e32 v50, 16, v56
	v_and_b32_e32 v51, 0xffff0000, v56
	v_pk_fma_f32 v[42:43], v[16:17], v[42:43], v[48:49]
	v_lshlrev_b32_e32 v38, 16, v39
	v_and_b32_e32 v39, 0xffff0000, v39
	v_pk_fma_f32 v[42:43], v[20:21], v[50:51], v[42:43]
	v_lshlrev_b32_e32 v48, 16, v44
	v_pk_mul_f32 v[42:43], v[42:43], v[38:39]
	v_lshlrev_b32_e32 v38, 16, v100
	v_and_b32_e32 v39, 0xffff0000, v100
	v_and_b32_e32 v49, 0xffff0000, v44
	v_pk_mul_f32 v[38:39], v[2:3], v[38:39]
	v_lshlrev_b32_e32 v50, 16, v55
	v_and_b32_e32 v51, 0xffff0000, v55
	v_pk_fma_f32 v[38:39], v[10:11], v[48:49], v[38:39]
	v_pk_mul_f32 v[46:47], v[46:47], v[52:53]
	v_lshlrev_b32_e32 v52, 16, v40
	v_and_b32_e32 v53, 0xffff0000, v40
	v_pk_fma_f32 v[38:39], v[22:23], v[50:51], v[38:39]
	v_lshlrev_b32_e32 v44, 16, v45
	v_pk_mul_f32 v[48:49], v[38:39], v[52:53]
	v_lshlrev_b32_e32 v38, 16, v98
	v_and_b32_e32 v39, 0xffff0000, v98
	v_and_b32_e32 v45, 0xffff0000, v45
	v_pk_mul_f32 v[38:39], v[4:5], v[38:39]
	v_lshlrev_b32_e32 v50, 16, v54
	v_and_b32_e32 v51, 0xffff0000, v54
	v_pk_fma_f32 v[38:39], v[12:13], v[44:45], v[38:39]
	v_lshlrev_b32_e32 v40, 16, v41
	v_and_b32_e32 v41, 0xffff0000, v41
	v_pk_fma_f32 v[38:39], v[24:25], v[50:51], v[38:39]
	v_ashrrev_i32_e32 v83, 31, v82
	v_pk_mul_f32 v[44:45], v[38:39], v[40:41]
	v_cvt_pk_bf16_f32 v39, v42, v43
	v_lshlrev_b64 v[42:43], 11, v[82:83]
	v_cvt_pk_bf16_f32 v38, v46, v47
	v_cvt_pk_bf16_f32 v40, v48, v49
	v_cvt_pk_bf16_f32 v41, v44, v45
	v_lshl_add_u64 v[42:43], v[78:79], 0, v[42:43]
	global_store_dwordx4 v[42:43], v[38:41], off offset:1024 sc1
	s_and_b64 exec, exec, vcc
	s_cbranch_execz .LBB0_757
	v_cmp_ne_u32_e32 vcc, v92, v81
	s_waitcnt vmcnt(5)
	v_lshlrev_b32_e32 v40, 16, v26
	v_and_b32_e32 v41, 0xffff0000, v26
	s_waitcnt vmcnt(4)
	v_cndmask_b32_e32 v44, 0, v35, vcc
	v_cndmask_b32_e32 v39, 0, v34, vcc
	v_lshlrev_b32_e32 v34, 16, v97
	v_and_b32_e32 v35, 0xffff0000, v97
	v_cndmask_b32_e32 v42, 0, v37, vcc
	v_cndmask_b32_e32 v43, 0, v36, vcc
	v_lshlrev_b32_e32 v36, 16, v30
	v_and_b32_e32 v37, 0xffff0000, v30
	v_pk_mul_f32 v[34:35], v[6:7], v[34:35]
	v_lshlrev_b32_e32 v38, 16, v39
	v_pk_fma_f32 v[34:35], v[14:15], v[36:37], v[34:35]
	v_lshlrev_b32_e32 v36, 16, v96
	v_and_b32_e32 v37, 0xffff0000, v96
	v_and_b32_e32 v39, 0xffff0000, v39
	v_lshlrev_b32_e32 v30, 16, v31
	v_and_b32_e32 v31, 0xffff0000, v31
	v_pk_mul_f32 v[36:37], v[8:9], v[36:37]
	v_pk_fma_f32 v[34:35], v[18:19], v[38:39], v[34:35]
	v_lshlrev_b32_e32 v38, 16, v44
	v_and_b32_e32 v39, 0xffff0000, v44
	v_pk_fma_f32 v[30:31], v[16:17], v[30:31], v[36:37]
	v_lshlrev_b32_e32 v26, 16, v27
	v_and_b32_e32 v27, 0xffff0000, v27
	v_pk_fma_f32 v[30:31], v[20:21], v[38:39], v[30:31]
	v_lshlrev_b32_e32 v36, 16, v32
	v_pk_mul_f32 v[30:31], v[30:31], v[26:27]
	v_lshlrev_b32_e32 v26, 16, v94
	v_and_b32_e32 v27, 0xffff0000, v94
	v_and_b32_e32 v37, 0xffff0000, v32
	v_pk_mul_f32 v[26:27], v[2:3], v[26:27]
	v_lshlrev_b32_e32 v38, 16, v43
	v_and_b32_e32 v39, 0xffff0000, v43
	v_pk_fma_f32 v[26:27], v[10:11], v[36:37], v[26:27]
	v_pk_mul_f32 v[34:35], v[34:35], v[40:41]
	v_lshlrev_b32_e32 v40, 16, v28
	v_and_b32_e32 v41, 0xffff0000, v28
	v_pk_fma_f32 v[26:27], v[22:23], v[38:39], v[26:27]
	v_lshlrev_b32_e32 v32, 16, v33
	v_pk_mul_f32 v[36:37], v[26:27], v[40:41]
	v_lshlrev_b32_e32 v26, 16, v93
	v_and_b32_e32 v27, 0xffff0000, v93
	v_and_b32_e32 v33, 0xffff0000, v33
	v_pk_mul_f32 v[26:27], v[4:5], v[26:27]
	v_lshlrev_b32_e32 v38, 16, v42
	v_and_b32_e32 v39, 0xffff0000, v42
	v_pk_fma_f32 v[26:27], v[12:13], v[32:33], v[26:27]
	v_lshlrev_b32_e32 v28, 16, v29
	v_and_b32_e32 v29, 0xffff0000, v29
	v_pk_fma_f32 v[26:27], v[24:25], v[38:39], v[26:27]
	v_ashrrev_i32_e32 v81, 31, v80
	v_pk_mul_f32 v[32:33], v[26:27], v[28:29]
	v_cvt_pk_bf16_f32 v27, v30, v31
	v_lshlrev_b64 v[30:31], 11, v[80:81]
	v_cvt_pk_bf16_f32 v26, v34, v35
	v_cvt_pk_bf16_f32 v28, v36, v37
	v_cvt_pk_bf16_f32 v29, v32, v33
	v_lshl_add_u64 v[30:31], v[78:79], 0, v[30:31]
	global_store_dwordx4 v[30:31], v[26:29], off offset:1024 sc1
	s_branch .LBB0_757
